# code placement: the five GEMM K-loop heads aligned to 64 bytes (on top of the pool fast path)
# speedup vs baseline: 1.0053x; 1.0053x over previous
.Lprio_skip_0:
	.p2align	6
